# attention: first unit of each workgroup is its local index (no queue draw / broadcast), queue serves units 128..255; on top of v123
# baseline (speedup 1.0000x reference)
; __device__ __forceinline__ void attn_issue(Frame& F, int id, KvRegs& R) {
;     const int b = id >> 5, n = (id >> 1) & 15, kvh = id & 1, key0 = 128 * (n - 1), tid = F.tid;
;     const bf16* Kb = (const bf16*)(F.ws + WS_K); const bf16* VT = (const bf16*)(F.ws + WS_VT);
;     const v4u zero4 = (v4u){0u, 0u, 0u, 0u};
; #pragma unroll
;     for (int i = 0; i < 6; ++i) { const int p = tid + 512 * i, row = p >> 3, pc = p & 7, pos = key0 + row;
;         R.k[i] = zero4; if (pos >= 0 && pos < SEQ) R.k[i] = *(const v4u*)(Kb + ((size_t)(b * SEQ + pos)) * 128 + kvh * 64 + pc * 8); }
; __device__ __forceinline__ void p2_mix(Frame& F, int slot) {
;     ...
;     constexpr int NU = 512 / NDOM; const int base = NU * F.dom;
;     att::KvRegs R;
;     if (F.tid == 0) F.MISC[16] = __hip_atomic_fetch_add(F.ctl + CW_ATTQ + 64 * F.dom, 1u, RLX_AGENT);
;     __syncthreads();
;     int id = (int)F.MISC[16];
;     __syncthreads();
;     if (id < NU) att::attn_issue(F, base + id, R);
.LBB0_513:
	v_cmp_eq_u32_e64 s[0:1], 0, v0
	s_waitcnt vmcnt(0) lgkmcnt(0)
	s_barrier
	v_mov_b32_e32 v1, s74
	s_mov_b32 s33, s74
	s_lshl_b32 s11, s10, 8
	v_lshlrev_b32_e32 v8, 4, v0
	s_mov_b64 s[2:3], exec
	s_add_i32 s4, s33, s11
	s_ashr_i32 s14, s4, 5
	s_lshl_b32 s4, s4, 6
	s_and_b32 s16, s4, 0x780
	s_and_b32 s15, s4, 64
	s_addk_i32 s16, 0xff80
	s_lshl_b32 s17, s14, 11
	s_lshl_b32 s4, s15, 1
	s_add_u32 s4, s30, s4
	s_addc_u32 s5, s31, 0
	v_and_b32_e32 v114, 0x70, v8
	v_mov_b32_e32 v115, 0
	v_lshl_add_u64 v[2:3], s[4:5], 0, v[114:115]
	s_mov_b64 s[4:5], 0x9000000
	s_cmpk_gt_u32 s16, 0x7ff
	v_lshl_add_u64 v[2:3], v[2:3], 0, s[4:5]
	s_cbranch_scc1 .LBB0_521
	v_lshrrev_b32_e32 v1, 3, v0
	v_or_b32_e32 v1, s16, v1
	v_or_b32_e32 v4, s17, v1
	v_ashrrev_i32_e32 v5, 31, v4
	v_lshlrev_b64 v[4:5], 8, v[4:5]
	v_lshl_add_u64 v[4:5], v[2:3], 0, v[4:5]
	global_load_dwordx4 v[114:117], v[4:5], off
	s_branch .LBB0_522

; #define PROBE_BEGIN(id) unsigned long long pb_t0_##id = 0; if (PROBE_SEC == (id)) pb_t0_##id = __builtin_amdgcn_s_memrealtime();
; #define PROBE_END(id) if (PROBE_SEC == (id)) { const unsigned long long pb_t1_ = __builtin_amdgcn_s_memrealtime(), pb_dt_ = pb_t1_ - pb_t0_##id; while (__builtin_amdgcn_s_memrealtime() - pb_t1_ < pb_dt_) __builtin_amdgcn_s_sleep(4); }
; #define LAS __attribute__((address_space(3)))
; __device__ __forceinline__ void attn_commit(Frame& F, int id, const KvRegs& R) {
;     LAS unsigned char* lds = F.lds; const int tid = F.tid, kvh = id & 1;
;     PROBE_BEGIN(3)
; #pragma unroll
;     for (int i = 0; i < 6; ++i) { const int p = tid + 512 * i, row = p >> 3, pc = p & 7; *(LAS v4u*)(lds + OFF_K + row * KROW + pc * 16) = R.k[i]; }
; #pragma unroll
;     for (int i = 0; i < 6; ++i) { const int p = tid + 512 * i, d = p / 48, pc = p - d * 48;
;         *(LAS v2u*)(lds + OFF_V + d * VROW + pc * 16) = (v2u){R.v[i].x, R.v[i].y}; *(LAS v2u*)(lds + OFF_V + d * VROW + pc * 16 + 8) = (v2u){R.v[i].z, R.v[i].w}; }
;     LAS f32x4* BT4 = (LAS f32x4*)(lds + OFF_B);
;     {   const f32x4* src = (const f32x4*)(F.ws + WS_BT4) + kvh * 4 * NBT;
; #pragma unroll
;         for (int i = 0; i < 3; ++i) BT4[tid + 512 * i] = src[tid + 512 * i]; }
;     __syncthreads();
;     PROBE_END(3)
; }
; __device__ __forceinline__ void p2_mix(Frame& F, int slot) {
;     ...
;         if (F.tid == 0) F.MISC[16] = __hip_atomic_fetch_add(F.ctl + CW_ATTQ + 64 * F.dom, 1u, RLX_AGENT);
;         __syncthreads();
;         const int nid = (int)F.MISC[16];
;         if (nid < NU) att::attn_issue(F, base + nid, R);
.Lqd_join:
	s_waitcnt vmcnt(5)
	ds_write_b128 v230, v[114:117]
	ds_write_b128 v231, v[118:121]
	s_waitcnt vmcnt(4)
	ds_write_b128 v232, v[126:129]
	ds_write_b128 v233, v[122:125]
	ds_write_b128 v234, v[130:133]
	ds_write_b128 v235, v[134:137]
	ds_write2_b64 v236, v[138:139], v[140:141] offset1:1
	ds_write2_b64 v237, v[142:143], v[144:145] offset1:1
	ds_write2_b64 v238, v[146:147], v[148:149] offset1:1
	ds_write2_b64 v239, v[150:151], v[152:153] offset1:1
	ds_write2_b64 v240, v[154:155], v[156:157] offset1:1
	ds_write2_b64 v241, v[158:159], v[160:161] offset1:1
	s_waitcnt vmcnt(3)
	ds_write_b128 v218, v[4:7]
	s_waitcnt vmcnt(2)
	ds_write_b128 v219, v[8:11]
	s_waitcnt vmcnt(1)
	ds_write_b128 v220, v[12:15]
	s_and_saveexec_b64 s[2:3], s[0:1]
	s_waitcnt vmcnt(0)
	v_add_u32_e32 v250, 0x80, v250
	v_mov_b32_e32 v3, s41
	ds_write_b32 v3, v250
	s_or_b64 exec, exec, s[2:3]
	v_mov_b32_e32 v3, s41
	s_waitcnt lgkmcnt(0)
	s_barrier
	ds_read_b32 v3, v3
	s_waitcnt lgkmcnt(0)
	v_cmp_lt_i32_e64 s[2:3], s42, v3
	v_readfirstlane_b32 s44, v3
	s_and_b64 vcc, exec, s[2:3]
	s_cbranch_vccnz .LBB0_574
	s_add_i32 s4, s44, s11
	s_ashr_i32 s23, s4, 5
	s_lshl_b32 s4, s4, 6
	s_and_b32 s22, s4, 0x780
	s_and_b32 s46, s4, 64
	s_addk_i32 s22, 0xff80
	s_lshl_b32 s47, s23, 11
	s_lshl_b32 s14, s46, 1
	s_cmpk_gt_u32 s22, 0x7ff
	v_lshl_add_u64 v[6:7], v[194:195], 0, s[14:15]
	s_cbranch_scc1 .LBB0_552
	v_or_b32_e32 v3, s22, v1
	v_or_b32_e32 v4, s47, v3
	v_ashrrev_i32_e32 v5, 31, v4
	v_lshlrev_b64 v[4:5], 8, v[4:5]
	v_lshl_add_u64 v[4:5], v[6:7], 0, v[4:5]
	global_load_dwordx4 v[114:117], v[4:5], off
	s_branch .LBB0_553
